# v8 + static s_setprio 1 for waves 4..7 inside the attention loops
# speedup vs baseline: 1.0074x; 1.0041x over previous
; __global__ void __launch_bounds__(NTHREADS, 2) mk_fwd(Params p_arg) {
;     ...
;     for (int ph = ph_lo; ph < ph_hi; ++ph) {
.LBB0_3:
	s_setprio 0
	v_readlane_b32 s2, v253, 2
	s_add_i32 s68, s68, 1
	v_readlane_b32 s3, v253, 3
	v_readlane_b32 s24, v254, 2
	s_cmp_ge_i32 s68, s3
	v_readlane_b32 s25, v254, 3
	v_readlane_b32 s28, v253, 62
	v_readlane_b32 s29, v253, 63
	s_cbranch_scc1 .LBB0_1001

; #define SBAR() __builtin_amdgcn_sched_barrier(0)
; #define SLOAD(i, j) do { const long rb_ = KROW(j); sr_[i].vs0 = *(const bf16x8*)(a.V + (rb_ + sr) * LDV + sc); sr_[i].vs1 = *(const bf16x8*)(a.V + (rb_ + 32 + sr) * LDV + sc); \
;     _Pragma("unroll") for (int c_ = 0; c_ < KCH; ++c_) sr_[i].ks[c_] = *(const bf16x8*)(kptr[c_] + rb_ * kld[c_]); } while (0)
; #define SWRITE(b, i) do { *(bf16x8*)(V_lds + (b) * SHM_V + vst0) = sr_[i].vs0; *(bf16x8*)(V_lds + (b) * SHM_V + vst1) = sr_[i].vs1; \
;     _Pragma("unroll") for (int c_ = 0; c_ < KCH; ++c_) *(bf16x8*)(K_lds + (b) * SHM_K + kwo[c_]) = sr_[i].ks[c_]; } while (0)
; #define RESC(al) do { if (__any((al) < 1.f)) { if (hi == 0) al_l[r32] = (al); asm volatile("s_waitcnt lgkmcnt(0)" ::: "memory"); \
;     _Pragma("unroll") for (int d = 0; d < 4; ++d) _Pragma("unroll") for (int r = 0; r < 16; ++r) o[d][r] *= al_l[crow(r, hi)]; } } while (0)
; template <int DQK, int DK1, int LDQ, int LDK, int LDKR, int LDV, int NQL, int SDEPTH>
; __device__ __forceinline__ void attn_core(const AttnArgs& a, char* lds, f32x16 (&o)[4]) {
;     ...
;     for (int j = 1; j + 1 < NT; j += 2) {
;         SBAR(); QKT(pB0, pB1, K_lds + SHM_K);
;         finishSM(pA0, pA1, alA, l_reg, pa0, pa1, pa2, pa3); SBAR();
;         SLOAD(SO, j + SDEPTH); SBAR();
;         pv_d0(o, vb0, pa0, pa1, pa2, pa3); partialSM(pB0, pB1, m_reg, mnB, alB, a.C, a.thr);
;         __syncthreads(); SWRITE(0, SE);
;         RESC(alB); __syncthreads();
;         SBAR(); QKT(pA0, pA1, K_lds);
;         finishSM(pB0, pB1, alB, l_reg, pa0, pa1, pa2, pa3); SBAR();
;         if (SDEPTH == 1 || j + 3 < NT) SLOAD(SE, j + 1 + SDEPTH); SBAR();
;         pv_d0(o, vb0 + SHM_V, pa0, pa1, pa2, pa3); partialSM(pA0, pA1, m_reg, mnA, alA, a.C, a.thr);
;         __syncthreads(); SWRITE(1, SO);
;         RESC(alA); __syncthreads();
;     }
.LBB0_171:
	v_readfirstlane_b32 s98, v159
	s_cmp_gt_u32 s98, 0xff
	s_cbranch_scc0 .Lprio_d
	s_setprio 1
